# D and MLA attention loops unrolled x2 over the LDS double buffer: immediate buffer offsets, no per-iteration base arithmetic, loop control halved
# speedup vs baseline: 1.0168x; 1.0139x over previous
; #define ALAS __attribute__((address_space(3)))
; template <bool SUB> __device__ __forceinline__ void attn_unit_r2(const AU& u, ALAS unsigned char* lds, float mb2) {
;     ...
;     int tid_o = threadIdx.x; asm volatile("" : "+v"(tid_o));
;     const int tid = tid_o, lane = tid & 63, wid = __builtin_amdgcn_readfirstlane(tid >> 6), r = lane & 31, h = lane >> 5;
;     const int hl = wid / u.wph, qs = u.q0 + 64 * (wid % u.wph);
;     bf16x8 qa[4], qb[4];
;     { const bf16_t* qp = u.Q + (size_t)hl * u.qhs + (size_t)(qs + r) * u.qrs + h * 8;
; #pragma unroll
;       for (int d0 = 0; d0 < 4; ++d0) { qa[d0] = *(const bf16x8*)(qp + d0 * 16); qb[d0] = *(const bf16x8*)(qp + (size_t)32 * u.qrs + d0 * 16); } }
;     const int NT = u.nsub >> 6;
;     const int kr0 = tid >> 3, kc0 = tid & 7;
;     const bf16_t* kg0 = u.K + (size_t)kr0 * u.krs + kc0 * 8; const bf16_t* vg = u.V + (size_t)kr0 * u.vrs + kc0 * 8;
;     const int kl0 = kr0 * KP + kc0 * 16, vl = V_OFF + kr0 * VP + kc0 * 16;
;     f32x16 oa0, oa1, ob0, ob1, negm;
; #pragma unroll
;     for (int i = 0; i < 16; ++i) { oa0[i] = 0.f; oa1[i] = 0.f; ob0[i] = 0.f; ob1[i] = 0.f; negm[i] = SUB ? -mb2 : 0.f; }
;     float la = 0.f, lb = 0.f;
;     u32x4 rk = *(const u32x4*)kg0, rv = *(const u32x4*)vg;
;     *(ALAS u32x4*)(lds + kl0) = rk; *(ALAS u32x4*)(lds + vl) = rv;
;     __syncthreads();
.LBB0_169:
	s_and_b64 vcc, exec, s[52:53]
	s_cbranch_vccz .LBB0_117
	s_and_saveexec_b64 s[20:21], s[38:39]
	s_xor_b64 s[52:53], exec, s[20:21]
	s_cbranch_execz .LBB0_178
	v_mov_b32_e32 v22, v171
	v_mov_b64_e32 v[16:17], s[22:23]
	v_readfirstlane_b32 s2, v22
	s_ashr_i32 s2, s2, 6
	s_lshr_b32 s7, s2, 31
	s_add_i32 s7, s2, s7
	s_ashr_i32 s54, s7, 1
	s_and_b32 s7, s7, 0x3fffffe
	v_ashrrev_i32_e32 v23, 3, v22
	s_movk_i32 s30, 0xc00
	v_lshlrev_b32_e32 v18, 4, v22
	v_mov_b64_e32 v[20:21], s[4:5]
	s_sub_i32 s2, s2, s7
	v_mad_i64_i32 v[16:17], s[20:21], v23, s30, v[16:17]
	v_and_b32_e32 v18, 0x70, v18
	v_mad_i64_i32 v[20:21], s[20:21], v23, s30, v[20:21]
	v_mov_b32_e32 v19, v169
	s_lshl_b32 s2, s2, 6
	v_lshl_add_u64 v[20:21], v[20:21], 0, v[18:19]
	v_lshl_add_u64 v[16:17], v[16:17], 0, v[18:19]
	v_and_b32_e32 v19, 31, v22
	s_ashr_i32 s55, s54, 31
	s_add_i32 s2, s2, s79
	global_load_dwordx4 v[128:131], v[20:21], off
	global_load_dwordx4 v[132:135], v[16:17], off
	s_lshl_b64 s[54:55], s[54:55], 7
	v_or_b32_e32 v16, s2, v19
	s_movk_i32 s7, 0x600
	s_add_u32 s54, s48, s54
	v_mul_lo_u32 v16, v16, s7
	v_bfe_u32 v24, v22, 5, 1
	s_addc_u32 s55, s49, s55
	v_ashrrev_i32_e32 v17, 31, v16
	v_lshlrev_b32_e32 v168, 4, v24
	v_lshl_add_u64 v[16:17], v[16:17], 1, s[54:55]
	v_lshl_add_u64 v[16:17], v[16:17], 0, v[168:169]
	s_mov_b32 s7, 0x18000
	v_add_co_u32_e32 v20, vcc, s7, v16
	v_bfe_u32 v25, v22, 2, 2
	s_nop 0
	v_addc_co_u32_e32 v21, vcc, 0, v17, vcc
	global_load_dwordx4 v[136:139], v[16:17], off
	global_load_dwordx4 v[140:143], v[16:17], off offset:32
	global_load_dwordx4 v[144:147], v[16:17], off offset:64
	global_load_dwordx4 v[148:151], v[16:17], off offset:96
	global_load_dwordx4 v[152:155], v[20:21], off
	global_load_dwordx4 v[156:159], v[20:21], off offset:32
	global_load_dwordx4 v[160:163], v[20:21], off offset:64
	global_load_dwordx4 v[164:167], v[20:21], off offset:96
	v_lshlrev_b32_e32 v16, 1, v22
	v_lshlrev_b32_e32 v17, 3, v22
	s_movk_i32 s7, 0x90
	v_mul_u32_u24_e32 v19, 0x90, v19
	v_lshl_or_b32 v21, v24, 2, v25
	v_and_b32_e32 v22, 32, v16
	v_and_b32_e32 v24, 24, v17
	v_mad_i64_i32 v[16:17], s[54:55], v23, s30, 0
	v_mul_lo_u32 v20, v23, s7
	v_add3_u32 v168, 0, v19, v168
	v_mad_u32_u24 v19, v21, s7, 0
	v_or_b32_e32 v16, v16, v18
	v_mov_b32_e32 v48, 0
	v_add3_u32 v220, v18, v20, 0
	v_add3_u32 v221, v19, v22, v24
	v_lshl_add_u64 v[18:19], s[4:5], 0, v[16:17]
	v_lshl_add_u64 v[16:17], s[22:23], 0, v[16:17]
	s_mov_b32 s21, 0
	v_mov_b32_e32 v49, v48
	v_mov_b32_e32 v50, v48
	v_mov_b32_e32 v51, v48
	v_mov_b32_e32 v52, v48
	v_mov_b32_e32 v53, v48
	v_mov_b32_e32 v54, v48
	v_mov_b32_e32 v55, v48
	v_mov_b32_e32 v56, v48
	v_mov_b32_e32 v57, v48
	v_mov_b32_e32 v58, v48
	v_lshl_add_u64 v[174:175], v[18:19], 0, s[12:13]
	v_lshl_add_u64 v[176:177], v[16:17], 0, s[12:13]
	s_lshr_b32 s7, s78, 6
	v_mov_b32_e32 v59, v48
	v_mov_b32_e32 v60, v48
	v_mov_b32_e32 v61, v48
	v_mov_b32_e32 v62, v48
	v_mov_b32_e32 v63, v48
	v_mov_b32_e32 v64, v48
	v_mov_b32_e32 v65, v48
	v_mov_b32_e32 v66, v48
	v_mov_b32_e32 v67, v48
	v_mov_b32_e32 v68, v48
	v_mov_b32_e32 v69, v48
	v_mov_b32_e32 v70, v48
	v_mov_b32_e32 v71, v48
	v_mov_b32_e32 v72, v48
	v_mov_b32_e32 v73, v48
	v_mov_b32_e32 v74, v48
	v_mov_b32_e32 v75, v48
	v_mov_b32_e32 v76, v48
	v_mov_b32_e32 v77, v48
	v_mov_b32_e32 v78, v48
	v_mov_b32_e32 v79, v48
	v_mov_b32_e32 v16, v48
	v_mov_b32_e32 v17, v48
	v_mov_b32_e32 v18, v48
	v_mov_b32_e32 v19, v48
	v_mov_b32_e32 v20, v48
	v_mov_b32_e32 v21, v48
	v_mov_b32_e32 v22, v48
	v_mov_b32_e32 v23, v48
	v_mov_b32_e32 v24, v48
	v_mov_b32_e32 v25, v48
	v_mov_b32_e32 v26, v48
	v_mov_b32_e32 v27, v48
	v_mov_b32_e32 v28, v48
	v_mov_b32_e32 v29, v48
	v_mov_b32_e32 v30, v48
	v_mov_b32_e32 v31, v48
	v_mov_b32_e32 v32, v48
	v_mov_b32_e32 v33, v48
	v_mov_b32_e32 v34, v48
	v_mov_b32_e32 v35, v48
	v_mov_b32_e32 v36, v48
	v_mov_b32_e32 v37, v48
	v_mov_b32_e32 v38, v48
	v_mov_b32_e32 v39, v48
	v_mov_b32_e32 v40, v48
	v_mov_b32_e32 v41, v48
	v_mov_b32_e32 v42, v48
	v_mov_b32_e32 v43, v48
	v_mov_b32_e32 v44, v48
	v_mov_b32_e32 v45, v48
	v_mov_b32_e32 v46, v48
	v_mov_b32_e32 v47, v48
	v_mov_b32_e32 v172, v48
	v_mov_b32_e32 v173, v48
	v_mov_b32_e32 v242, v48
	v_mov_b32_e32 v243, v48
	v_mov_b32_e32 v112, v48
	v_mov_b32_e32 v113, v48
	v_mov_b32_e32 v114, v48
	v_mov_b32_e32 v115, v48
	v_mov_b32_e32 v116, v48
	v_mov_b32_e32 v117, v48
	v_mov_b32_e32 v118, v48
	v_mov_b32_e32 v119, v48
	v_mov_b32_e32 v120, v48
	v_mov_b32_e32 v121, v48
	v_mov_b32_e32 v122, v48
	v_mov_b32_e32 v123, v48
	v_mov_b32_e32 v124, v48
	v_mov_b32_e32 v125, v48
	v_mov_b32_e32 v126, v48
	v_mov_b32_e32 v127, v48
	v_mov_b32_e32 v0, v48
	v_mov_b32_e32 v1, v48
	v_mov_b32_e32 v2, v48
	v_mov_b32_e32 v3, v48
	v_mov_b32_e32 v4, v48
	v_mov_b32_e32 v5, v48
	v_mov_b32_e32 v6, v48
	v_mov_b32_e32 v7, v48
	v_mov_b32_e32 v8, v48
	v_mov_b32_e32 v9, v48
	v_mov_b32_e32 v10, v48
	v_mov_b32_e32 v11, v48
	v_mov_b32_e32 v12, v48
	v_mov_b32_e32 v13, v48
	v_mov_b32_e32 v14, v48
	v_mov_b32_e32 v15, v48
	v_mov_b32_e32 v80, v48
	v_mov_b32_e32 v81, v48
	v_mov_b32_e32 v82, v48
	v_mov_b32_e32 v83, v48
	v_mov_b32_e32 v84, v48
	v_mov_b32_e32 v85, v48
	v_mov_b32_e32 v86, v48
	v_mov_b32_e32 v87, v48
	v_mov_b32_e32 v88, v48
	v_mov_b32_e32 v89, v48
	v_mov_b32_e32 v90, v48
	v_mov_b32_e32 v91, v48
	v_mov_b32_e32 v92, v48
	v_mov_b32_e32 v93, v48
	v_mov_b32_e32 v94, v48
	v_mov_b32_e32 v95, v48
	v_mov_b32_e32 v96, v48
	v_mov_b32_e32 v97, v48
	v_mov_b32_e32 v98, v48
	v_mov_b32_e32 v99, v48
	v_mov_b32_e32 v100, v48
	v_mov_b32_e32 v101, v48
	v_mov_b32_e32 v102, v48
	v_mov_b32_e32 v103, v48
	v_mov_b32_e32 v104, v48
	v_mov_b32_e32 v105, v48
	v_mov_b32_e32 v106, v48
	v_mov_b32_e32 v107, v48
	v_mov_b32_e32 v108, v48
	v_mov_b32_e32 v109, v48
	v_mov_b32_e32 v110, v48
	v_mov_b32_e32 v111, v48
	v_mov_b32_e32 v178, v48
	v_mov_b32_e32 v179, v48
	v_mov_b32_e32 v180, v48
	v_mov_b32_e32 v181, v48
	v_mov_b32_e32 v182, v48
	v_mov_b32_e32 v183, v48
	v_mov_b32_e32 v184, v48
	v_mov_b32_e32 v185, v48
	v_mov_b32_e32 v186, v48
	v_mov_b32_e32 v187, v48
	v_mov_b32_e32 v188, v48
	v_mov_b32_e32 v189, v48
	v_mov_b32_e32 v190, v48
	v_mov_b32_e32 v191, v48
	v_mov_b32_e32 v192, v48
	v_mov_b32_e32 v193, v48
	v_mov_b32_e32 v194, v48
	v_mov_b32_e32 v195, v48
	v_mov_b32_e32 v196, v48
	v_mov_b32_e32 v197, v48
	v_mov_b32_e32 v210, v48
	v_mov_b32_e32 v211, v48
	v_mov_b32_e32 v212, v48
	v_mov_b32_e32 v213, v48
	v_mov_b32_e32 v238, v48
	v_mov_b32_e32 v239, v48
	v_mov_b32_e32 v240, v48
	v_mov_b32_e32 v241, v48
	v_mov_b32_e32 v248, v48
	v_mov_b32_e32 v249, v48
	v_mov_b32_e32 v250, v48
	v_mov_b32_e32 v251, v48
	s_waitcnt vmcnt(9)
	ds_write_b128 v220, v[128:131]
	s_waitcnt vmcnt(0)
	ds_write_b128 v220, v[132:135] offset:18432
	s_waitcnt lgkmcnt(0)
	s_barrier
	s_branch .Lr2n_topA
; #define ALAS __attribute__((address_space(3)))
; __device__ __forceinline__ s16x4 vtr(const ALAS unsigned char* p) { return __builtin_bit_cast(s16x4, __builtin_amdgcn_ds_read_tr16_b64_v4i16((ALAS s16x4*)p)); }
; #define AMFMA(a, b, c) __builtin_amdgcn_mfma_f32_32x32x16_bf16((a), (b), (c), 0, 0, 0)
; template <bool SUB> __device__ __forceinline__ void attn_unit_r2(const AU& u, ALAS unsigned char* lds, float mb2) {
;     ...
;         if (t + 1 < NT) { const size_t ro = (size_t)(t + 1) * 64; rk = *(const u32x4*)(kg0 + ro * u.krs); rv = *(const u32x4*)(vg + ro * u.vrs); }
;         {
;             const ALAS unsigned char* kb = lds + cur * KBUF + r * KP + h * 16;
;             const ALAS unsigned char* vb = lds + V_OFF + cur * VBUF + (4 * h + ((lane & 15) >> 2)) * VP + ((lane >> 4) & 1) * 32 + (lane & 3) * 8;
;             f32x16 Sa0 = negm, Sa1 = negm, Sb0 = negm, Sb1 = negm;
; #pragma unroll
;             for (int d0 = 0; d0 < 4; ++d0) {
;                 const bf16x8 k0 = *(const ALAS bf16x8*)(kb + d0 * 32), k1 = *(const ALAS bf16x8*)(kb + 32 * KP + d0 * 32);
;                 Sa0 = AMFMA(k0, qa[d0], Sa0); Sa1 = AMFMA(k1, qa[d0], Sa1); Sb0 = AMFMA(k0, qb[d0], Sb0); Sb1 = AMFMA(k1, qb[d0], Sb1);
;             }
;             bf16x8 paa[4], pab[4];
;     ...
;             R2_SOFT(Sa0, Sa1, paa, la);
;             R2_SOFT(Sb0, Sb1, pab, lb);
;     ...
; #pragma unroll
;             for (int ks = 0; ks < 4; ++ks) {
;                 const s16x4 lo0 = vtr(vb + ks * 16 * VP), hi0 = vtr(vb + (ks * 16 + 8) * VP), lo1 = vtr(vb + ks * 16 * VP + 64), hi1 = vtr(vb + (ks * 16 + 8) * VP + 64);
;                 const bf16x8 vf0 = __builtin_shufflevector(lo0, hi0, 0, 1, 2, 3, 4, 5, 6, 7), vf1 = __builtin_shufflevector(lo1, hi1, 0, 1, 2, 3, 4, 5, 6, 7);
;                 oa0 = AMFMA(paa[ks], vf0, oa0); oa1 = AMFMA(paa[ks], vf1, oa1); ob0 = AMFMA(pab[ks], vf0, ob0); ob1 = AMFMA(pab[ks], vf1, ob1);
.Lr2n_topA:
	global_load_dwordx4 v[128:131], v[174:175], off
	global_load_dwordx4 v[132:135], v[176:177], off
	ds_read_b128 v[222:225], v168 offset:0
	ds_read_b128 v[226:229], v168 offset:32
	ds_read_b128 v[230:233], v168 offset:64
	ds_read_b128 v[234:237], v168 offset:96
	v_mfma_f32_32x32x16_bf16 v[48:63], v[178:181], v[238:241], v[48:63]
	v_add_f32_e32 v172, v96, v172
	v_add_f32_e32 v173, v80, v173
	v_add_f32_e32 v172, v97, v172
	v_add_f32_e32 v173, v81, v173
	v_mfma_f32_32x32x16_bf16 v[64:79], v[178:181], v[248:251], v[64:79]
	v_add_f32_e32 v172, v98, v172
	v_add_f32_e32 v173, v82, v173
	v_add_f32_e32 v172, v99, v172
	v_add_f32_e32 v173, v83, v173
	ds_read_b128 v[178:181], v168 offset:4608
	v_mfma_f32_32x32x16_bf16 v[16:31], v[182:185], v[238:241], v[16:31]
	v_add_f32_e32 v172, v100, v172
	v_add_f32_e32 v173, v84, v173
	v_add_f32_e32 v172, v101, v172
	v_add_f32_e32 v173, v85, v173
	v_mfma_f32_32x32x16_bf16 v[32:47], v[182:185], v[248:251], v[32:47]
	v_add_f32_e32 v172, v102, v172
	v_add_f32_e32 v173, v86, v173
	v_add_f32_e32 v172, v103, v172
	v_add_f32_e32 v173, v87, v173
	ds_read_b128 v[182:185], v168 offset:4640
	v_mfma_f32_32x32x16_bf16 v[48:63], v[186:189], v[194:197], v[48:63]
	v_add_f32_e32 v172, v104, v172
	v_add_f32_e32 v173, v88, v173
	v_add_f32_e32 v172, v105, v172
	v_add_f32_e32 v173, v89, v173
	v_mfma_f32_32x32x16_bf16 v[64:79], v[186:189], v[210:213], v[64:79]
	v_add_f32_e32 v172, v106, v172
	v_add_f32_e32 v173, v90, v173
	v_add_f32_e32 v172, v107, v172
	v_add_f32_e32 v173, v91, v173
	ds_read_b128 v[186:189], v168 offset:4672
	v_mfma_f32_32x32x16_bf16 v[16:31], v[190:193], v[194:197], v[16:31]
	v_add_f32_e32 v172, v108, v172
	v_add_f32_e32 v173, v92, v173
	v_add_f32_e32 v172, v109, v172
	v_add_f32_e32 v173, v93, v173
	v_mfma_f32_32x32x16_bf16 v[32:47], v[190:193], v[210:213], v[32:47]
	v_add_f32_e32 v172, v110, v172
	v_add_f32_e32 v173, v94, v173
	v_add_f32_e32 v172, v111, v172
	v_add_f32_e32 v173, v95, v173
	ds_read_b128 v[190:193], v168 offset:4704
	s_waitcnt lgkmcnt(4)
	v_mfma_f32_32x32x16_bf16 v[96:111], v[222:225], v[136:139], 0
	v_lshl_add_u64 v[174:175], v[174:175], 0, s[12:13]
	v_add_f32_e32 v242, v112, v242
	v_add_f32_e32 v243, v0, v243
	v_add_f32_e32 v242, v113, v242
	v_add_f32_e32 v243, v1, v243
	v_add_f32_e32 v242, v114, v242
	v_mfma_f32_32x32x16_bf16 v[96:111], v[226:229], v[140:143], v[96:111]
	v_lshl_add_u64 v[176:177], v[176:177], 0, s[12:13]
	v_add_f32_e32 v243, v2, v243
	v_add_f32_e32 v242, v115, v242
	v_add_f32_e32 v243, v3, v243
	v_add_f32_e32 v242, v116, v242
	v_add_f32_e32 v243, v4, v243
	v_mfma_f32_32x32x16_bf16 v[96:111], v[230:233], v[144:147], v[96:111]
	v_add_f32_e32 v242, v117, v242
	v_add_f32_e32 v243, v5, v243
	v_add_f32_e32 v242, v118, v242
	v_add_f32_e32 v243, v6, v243
	v_add_f32_e32 v242, v119, v242
	v_add_f32_e32 v243, v7, v243
	v_mfma_f32_32x32x16_bf16 v[96:111], v[234:237], v[148:151], v[96:111]
	v_add_f32_e32 v242, v120, v242
	v_add_f32_e32 v243, v8, v243
	v_add_f32_e32 v242, v121, v242
	v_add_f32_e32 v243, v9, v243
	v_add_f32_e32 v242, v122, v242
	v_add_f32_e32 v243, v10, v243
	v_add_f32_e32 v242, v123, v242
	v_add_f32_e32 v243, v11, v243
	v_mfma_f32_32x32x16_bf16 v[80:95], v[222:225], v[152:155], 0
	v_add_f32_e32 v242, v124, v242
	v_add_f32_e32 v243, v12, v243
	v_add_f32_e32 v242, v125, v242
	v_add_f32_e32 v243, v13, v243
	v_add_f32_e32 v242, v126, v242
	v_add_f32_e32 v243, v14, v243
	v_add_f32_e32 v242, v127, v242
	v_add_f32_e32 v243, v15, v243
	v_mfma_f32_32x32x16_bf16 v[80:95], v[226:229], v[156:159], v[80:95]
	v_exp_f32_e32 v96, v96
	v_exp_f32_e32 v97, v97
	v_exp_f32_e32 v98, v98
	v_exp_f32_e32 v99, v99
	v_mfma_f32_32x32x16_bf16 v[80:95], v[230:233], v[160:163], v[80:95]
	v_exp_f32_e32 v100, v100
	v_exp_f32_e32 v101, v101
	v_exp_f32_e32 v102, v102
	v_exp_f32_e32 v103, v103
	v_mfma_f32_32x32x16_bf16 v[80:95], v[234:237], v[164:167], v[80:95]
	v_exp_f32_e32 v104, v104
	v_exp_f32_e32 v105, v105
	v_exp_f32_e32 v106, v106
	v_exp_f32_e32 v107, v107
	s_waitcnt lgkmcnt(0)
	v_mfma_f32_32x32x16_bf16 v[112:127], v[178:181], v[136:139], 0
	v_exp_f32_e32 v108, v108
	v_exp_f32_e32 v109, v109
	v_exp_f32_e32 v110, v110
	v_exp_f32_e32 v111, v111
	v_mfma_f32_32x32x16_bf16 v[112:127], v[182:185], v[140:143], v[112:127]
	v_cvt_pk_bf16_f32 v222, v96, v97
	v_cvt_pk_bf16_f32 v223, v98, v99
	v_cvt_pk_bf16_f32 v224, v100, v101
	v_cvt_pk_bf16_f32 v225, v102, v103
	v_exp_f32_e32 v80, v80
	v_exp_f32_e32 v81, v81
	v_mfma_f32_32x32x16_bf16 v[112:127], v[186:189], v[144:147], v[112:127]
	v_exp_f32_e32 v82, v82
	v_exp_f32_e32 v83, v83
	v_exp_f32_e32 v84, v84
	v_exp_f32_e32 v85, v85
	v_mfma_f32_32x32x16_bf16 v[112:127], v[190:193], v[148:151], v[112:127]
	v_exp_f32_e32 v86, v86
	v_exp_f32_e32 v87, v87
	v_cvt_pk_bf16_f32 v230, v104, v105
	v_cvt_pk_bf16_f32 v231, v106, v107
	v_cvt_pk_bf16_f32 v232, v108, v109
	v_cvt_pk_bf16_f32 v233, v110, v111
	v_mfma_f32_32x32x16_bf16 v[0:15], v[178:181], v[152:155], 0
	v_exp_f32_e32 v88, v88
	v_exp_f32_e32 v89, v89
	v_exp_f32_e32 v90, v90
	v_exp_f32_e32 v91, v91
	ds_read_b64_tr_b16 v[238:239], v221 offset:18432
	ds_read_b64_tr_b16 v[240:241], v221 offset:19584
	ds_read_b64_tr_b16 v[248:249], v221 offset:18496
	ds_read_b64_tr_b16 v[250:251], v221 offset:19648
	v_mfma_f32_32x32x16_bf16 v[0:15], v[182:185], v[156:159], v[0:15]
	v_exp_f32_e32 v92, v92
	v_exp_f32_e32 v93, v93
	v_exp_f32_e32 v94, v94
	v_exp_f32_e32 v95, v95
	v_mfma_f32_32x32x16_bf16 v[0:15], v[186:189], v[160:163], v[0:15]
	v_cvt_pk_bf16_f32 v226, v80, v81
	v_cvt_pk_bf16_f32 v227, v82, v83
	v_cvt_pk_bf16_f32 v228, v84, v85
	v_cvt_pk_bf16_f32 v229, v86, v87
	v_exp_f32_e32 v112, v112
	v_exp_f32_e32 v113, v113
	v_mfma_f32_32x32x16_bf16 v[0:15], v[190:193], v[164:167], v[0:15]
	v_exp_f32_e32 v114, v114
	v_exp_f32_e32 v115, v115
	v_exp_f32_e32 v116, v116
	v_exp_f32_e32 v117, v117
	ds_read_b64_tr_b16 v[194:195], v221 offset:20736
	ds_read_b64_tr_b16 v[196:197], v221 offset:21888
	ds_read_b64_tr_b16 v[210:211], v221 offset:20800
	ds_read_b64_tr_b16 v[212:213], v221 offset:21952
	s_waitcnt lgkmcnt(4)
; #define ALAS __attribute__((address_space(3)))
; __device__ __forceinline__ s16x4 vtr(const ALAS unsigned char* p) { return __builtin_bit_cast(s16x4, __builtin_amdgcn_ds_read_tr16_b64_v4i16((ALAS s16x4*)p)); }
; #define AMFMA(a, b, c) __builtin_amdgcn_mfma_f32_32x32x16_bf16((a), (b), (c), 0, 0, 0)
; template <bool SUB> __device__ __forceinline__ void attn_unit_r2(const AU& u, ALAS unsigned char* lds, float mb2) {
;     ...
;         if (t + 1 < NT) { const size_t ro = (size_t)(t + 1) * 64; rk = *(const u32x4*)(kg0 + ro * u.krs); rv = *(const u32x4*)(vg + ro * u.vrs); }
;         {
;             const ALAS unsigned char* kb = lds + cur * KBUF + r * KP + h * 16;
;             const ALAS unsigned char* vb = lds + V_OFF + cur * VBUF + (4 * h + ((lane & 15) >> 2)) * VP + ((lane >> 4) & 1) * 32 + (lane & 3) * 8;
;             f32x16 Sa0 = negm, Sa1 = negm, Sb0 = negm, Sb1 = negm;
; #pragma unroll
;             for (int d0 = 0; d0 < 4; ++d0) {
;                 const bf16x8 k0 = *(const ALAS bf16x8*)(kb + d0 * 32), k1 = *(const ALAS bf16x8*)(kb + 32 * KP + d0 * 32);
;                 Sa0 = AMFMA(k0, qa[d0], Sa0); Sa1 = AMFMA(k1, qa[d0], Sa1); Sb0 = AMFMA(k0, qb[d0], Sb0); Sb1 = AMFMA(k1, qb[d0], Sb1);
;             }
;             bf16x8 paa[4], pab[4];
;     ...
;             R2_SOFT(Sa0, Sa1, paa, la);
;             R2_SOFT(Sb0, Sb1, pab, lb);
;     ...
; #pragma unroll
;             for (int ks = 0; ks < 4; ++ks) {
;                 const s16x4 lo0 = vtr(vb + ks * 16 * VP), hi0 = vtr(vb + (ks * 16 + 8) * VP), lo1 = vtr(vb + ks * 16 * VP + 64), hi1 = vtr(vb + (ks * 16 + 8) * VP + 64);
;                 const bf16x8 vf0 = __builtin_shufflevector(lo0, hi0, 0, 1, 2, 3, 4, 5, 6, 7), vf1 = __builtin_shufflevector(lo1, hi1, 0, 1, 2, 3, 4, 5, 6, 7);
;                 oa0 = AMFMA(paa[ks], vf0, oa0); oa1 = AMFMA(paa[ks], vf1, oa1); ob0 = AMFMA(pab[ks], vf0, ob0); ob1 = AMFMA(pab[ks], vf1, ob1);
;             }
;         }
;         if (t + 1 < NT) { *(ALAS u32x4*)(lds + (cur ^ 1) * KBUF + kl0) = rk; *(ALAS u32x4*)(lds + (cur ^ 1) * VBUF + vl) = rv; }
;         __syncthreads();
	v_mfma_f32_32x32x16_bf16 v[48:63], v[222:225], v[238:241], v[48:63]
	v_exp_f32_e32 v118, v118
	v_exp_f32_e32 v119, v119
	v_exp_f32_e32 v120, v120
	v_exp_f32_e32 v121, v121
	v_mfma_f32_32x32x16_bf16 v[64:79], v[222:225], v[248:251], v[64:79]
	v_cvt_pk_bf16_f32 v234, v88, v89
	v_cvt_pk_bf16_f32 v235, v90, v91
	v_cvt_pk_bf16_f32 v236, v92, v93
	v_cvt_pk_bf16_f32 v237, v94, v95
	v_exp_f32_e32 v122, v122
	v_exp_f32_e32 v123, v123
	v_mfma_f32_32x32x16_bf16 v[16:31], v[226:229], v[238:241], v[16:31]
	v_exp_f32_e32 v124, v124
	v_exp_f32_e32 v125, v125
	v_exp_f32_e32 v126, v126
	v_exp_f32_e32 v127, v127
	v_mfma_f32_32x32x16_bf16 v[32:47], v[226:229], v[248:251], v[32:47]
	ds_read_b64_tr_b16 v[238:239], v221 offset:23040
	ds_read_b64_tr_b16 v[240:241], v221 offset:24192
	ds_read_b64_tr_b16 v[248:249], v221 offset:23104
	ds_read_b64_tr_b16 v[250:251], v221 offset:24256
	v_exp_f32_e32 v0, v0
	v_exp_f32_e32 v1, v1
	v_exp_f32_e32 v2, v2
	v_exp_f32_e32 v3, v3
	s_waitcnt lgkmcnt(4)
	v_mfma_f32_32x32x16_bf16 v[48:63], v[230:233], v[194:197], v[48:63]
	v_exp_f32_e32 v4, v4
	v_exp_f32_e32 v5, v5
	v_exp_f32_e32 v6, v6
	v_exp_f32_e32 v7, v7
	v_mfma_f32_32x32x16_bf16 v[64:79], v[230:233], v[210:213], v[64:79]
	v_cvt_pk_bf16_f32 v178, v112, v113
	v_cvt_pk_bf16_f32 v179, v114, v115
	v_cvt_pk_bf16_f32 v180, v116, v117
	v_cvt_pk_bf16_f32 v181, v118, v119
	v_exp_f32_e32 v8, v8
	v_exp_f32_e32 v9, v9
	v_mfma_f32_32x32x16_bf16 v[16:31], v[234:237], v[194:197], v[16:31]
	v_exp_f32_e32 v10, v10
	v_exp_f32_e32 v11, v11
	v_exp_f32_e32 v12, v12
	v_exp_f32_e32 v13, v13
	v_mfma_f32_32x32x16_bf16 v[32:47], v[234:237], v[210:213], v[32:47]
	ds_read_b64_tr_b16 v[194:195], v221 offset:25344
	ds_read_b64_tr_b16 v[196:197], v221 offset:26496
	ds_read_b64_tr_b16 v[210:211], v221 offset:25408
	ds_read_b64_tr_b16 v[212:213], v221 offset:26560
	v_exp_f32_e32 v14, v14
	v_exp_f32_e32 v15, v15
	v_cvt_pk_bf16_f32 v182, v0, v1
	v_cvt_pk_bf16_f32 v183, v2, v3
	v_cvt_pk_bf16_f32 v184, v4, v5
	v_cvt_pk_bf16_f32 v185, v6, v7
	v_cvt_pk_bf16_f32 v186, v120, v121
	v_cvt_pk_bf16_f32 v187, v122, v123
	v_cvt_pk_bf16_f32 v188, v124, v125
	v_cvt_pk_bf16_f32 v189, v126, v127
	v_cvt_pk_bf16_f32 v190, v8, v9
	v_cvt_pk_bf16_f32 v191, v10, v11
	v_cvt_pk_bf16_f32 v192, v12, v13
	v_cvt_pk_bf16_f32 v193, v14, v15
	s_waitcnt vmcnt(0)
	ds_write_b128 v220, v[128:131] offset:9216
	ds_write_b128 v220, v[132:135] offset:27648
	s_waitcnt lgkmcnt(0)
	s_barrier
.Lr2n_topB:
	s_add_i32 s20, s21, 2
	s_cmp_lt_u32 s20, s7
	s_cselect_b64 s[54:55], -1, 0
	s_cbranch_scc0 .Lr2n_noloadB
	global_load_dwordx4 v[128:131], v[174:175], off
	global_load_dwordx4 v[132:135], v[176:177], off
.Lr2n_noloadB:
	ds_read_b128 v[222:225], v168 offset:9216
	ds_read_b128 v[226:229], v168 offset:9248
	ds_read_b128 v[230:233], v168 offset:9280
	ds_read_b128 v[234:237], v168 offset:9312
	v_mfma_f32_32x32x16_bf16 v[48:63], v[178:181], v[238:241], v[48:63]
	v_add_f32_e32 v172, v96, v172
	v_add_f32_e32 v173, v80, v173
	v_add_f32_e32 v172, v97, v172
	v_add_f32_e32 v173, v81, v173
	v_mfma_f32_32x32x16_bf16 v[64:79], v[178:181], v[248:251], v[64:79]
	v_add_f32_e32 v172, v98, v172
	v_add_f32_e32 v173, v82, v173
	v_add_f32_e32 v172, v99, v172
	v_add_f32_e32 v173, v83, v173
	ds_read_b128 v[178:181], v168 offset:13824
	v_mfma_f32_32x32x16_bf16 v[16:31], v[182:185], v[238:241], v[16:31]
	v_add_f32_e32 v172, v100, v172
	v_add_f32_e32 v173, v84, v173
	v_add_f32_e32 v172, v101, v172
	v_add_f32_e32 v173, v85, v173
	v_mfma_f32_32x32x16_bf16 v[32:47], v[182:185], v[248:251], v[32:47]
	v_add_f32_e32 v172, v102, v172
	v_add_f32_e32 v173, v86, v173
	v_add_f32_e32 v172, v103, v172
	v_add_f32_e32 v173, v87, v173
	ds_read_b128 v[182:185], v168 offset:13856
	v_mfma_f32_32x32x16_bf16 v[48:63], v[186:189], v[194:197], v[48:63]
	v_add_f32_e32 v172, v104, v172
	v_add_f32_e32 v173, v88, v173
	v_add_f32_e32 v172, v105, v172
	v_add_f32_e32 v173, v89, v173
	v_mfma_f32_32x32x16_bf16 v[64:79], v[186:189], v[210:213], v[64:79]
	v_add_f32_e32 v172, v106, v172
	v_add_f32_e32 v173, v90, v173
	v_add_f32_e32 v172, v107, v172
	v_add_f32_e32 v173, v91, v173
	ds_read_b128 v[186:189], v168 offset:13888
	v_mfma_f32_32x32x16_bf16 v[16:31], v[190:193], v[194:197], v[16:31]
	v_add_f32_e32 v172, v108, v172
	v_add_f32_e32 v173, v92, v173
	v_add_f32_e32 v172, v109, v172
	v_add_f32_e32 v173, v93, v173
	v_mfma_f32_32x32x16_bf16 v[32:47], v[190:193], v[210:213], v[32:47]
	v_add_f32_e32 v172, v110, v172
	v_add_f32_e32 v173, v94, v173
	v_add_f32_e32 v172, v111, v172
	v_add_f32_e32 v173, v95, v173
	ds_read_b128 v[190:193], v168 offset:13920
	s_waitcnt lgkmcnt(4)
	v_mfma_f32_32x32x16_bf16 v[96:111], v[222:225], v[136:139], 0
	v_lshl_add_u64 v[174:175], v[174:175], 0, s[12:13]
	v_add_f32_e32 v242, v112, v242
	v_add_f32_e32 v243, v0, v243
	v_add_f32_e32 v242, v113, v242
	v_add_f32_e32 v243, v1, v243
	v_add_f32_e32 v242, v114, v242
	v_mfma_f32_32x32x16_bf16 v[96:111], v[226:229], v[140:143], v[96:111]
	v_lshl_add_u64 v[176:177], v[176:177], 0, s[12:13]
	v_add_f32_e32 v243, v2, v243
	v_add_f32_e32 v242, v115, v242
	v_add_f32_e32 v243, v3, v243
	v_add_f32_e32 v242, v116, v242
	v_add_f32_e32 v243, v4, v243
	v_mfma_f32_32x32x16_bf16 v[96:111], v[230:233], v[144:147], v[96:111]
	v_add_f32_e32 v242, v117, v242
	v_add_f32_e32 v243, v5, v243
	v_add_f32_e32 v242, v118, v242
	v_add_f32_e32 v243, v6, v243
	v_add_f32_e32 v242, v119, v242
	v_add_f32_e32 v243, v7, v243
	v_mfma_f32_32x32x16_bf16 v[96:111], v[234:237], v[148:151], v[96:111]
	v_add_f32_e32 v242, v120, v242
	v_add_f32_e32 v243, v8, v243
	v_add_f32_e32 v242, v121, v242
	v_add_f32_e32 v243, v9, v243
	v_add_f32_e32 v242, v122, v242
	v_add_f32_e32 v243, v10, v243
	v_add_f32_e32 v242, v123, v242
	v_add_f32_e32 v243, v11, v243
	v_mfma_f32_32x32x16_bf16 v[80:95], v[222:225], v[152:155], 0
	v_add_f32_e32 v242, v124, v242
	v_add_f32_e32 v243, v12, v243
	v_add_f32_e32 v242, v125, v242
	v_add_f32_e32 v243, v13, v243
	v_add_f32_e32 v242, v126, v242
	v_add_f32_e32 v243, v14, v243
	v_add_f32_e32 v242, v127, v242
	v_add_f32_e32 v243, v15, v243
	v_mfma_f32_32x32x16_bf16 v[80:95], v[226:229], v[156:159], v[80:95]
	v_exp_f32_e32 v96, v96
	v_exp_f32_e32 v97, v97
	v_exp_f32_e32 v98, v98
	v_exp_f32_e32 v99, v99
	v_mfma_f32_32x32x16_bf16 v[80:95], v[230:233], v[160:163], v[80:95]
	v_exp_f32_e32 v100, v100
	v_exp_f32_e32 v101, v101
	v_exp_f32_e32 v102, v102
	v_exp_f32_e32 v103, v103
	v_mfma_f32_32x32x16_bf16 v[80:95], v[234:237], v[164:167], v[80:95]
	v_exp_f32_e32 v104, v104
	v_exp_f32_e32 v105, v105
	v_exp_f32_e32 v106, v106
	v_exp_f32_e32 v107, v107
	s_waitcnt lgkmcnt(0)
; #define ALAS __attribute__((address_space(3)))
; __device__ __forceinline__ s16x4 vtr(const ALAS unsigned char* p) { return __builtin_bit_cast(s16x4, __builtin_amdgcn_ds_read_tr16_b64_v4i16((ALAS s16x4*)p)); }
; #define AMFMA(a, b, c) __builtin_amdgcn_mfma_f32_32x32x16_bf16((a), (b), (c), 0, 0, 0)
; template <bool SUB> __device__ __forceinline__ void attn_unit_r2(const AU& u, ALAS unsigned char* lds, float mb2) {
;     ...
;             R2_SOFT(Sa0, Sa1, paa, la);
;             R2_SOFT(Sb0, Sb1, pab, lb);
;     ...
; #pragma unroll
;             for (int ks = 0; ks < 4; ++ks) {
;                 const s16x4 lo0 = vtr(vb + ks * 16 * VP), hi0 = vtr(vb + (ks * 16 + 8) * VP), lo1 = vtr(vb + ks * 16 * VP + 64), hi1 = vtr(vb + (ks * 16 + 8) * VP + 64);
;                 const bf16x8 vf0 = __builtin_shufflevector(lo0, hi0, 0, 1, 2, 3, 4, 5, 6, 7), vf1 = __builtin_shufflevector(lo1, hi1, 0, 1, 2, 3, 4, 5, 6, 7);
;                 oa0 = AMFMA(paa[ks], vf0, oa0); oa1 = AMFMA(paa[ks], vf1, oa1); ob0 = AMFMA(pab[ks], vf0, ob0); ob1 = AMFMA(pab[ks], vf1, ob1);
;             }
;         }
;         if (t + 1 < NT) { *(ALAS u32x4*)(lds + (cur ^ 1) * KBUF + kl0) = rk; *(ALAS u32x4*)(lds + (cur ^ 1) * VBUF + vl) = rv; }
	v_mfma_f32_32x32x16_bf16 v[112:127], v[178:181], v[136:139], 0
	v_exp_f32_e32 v108, v108
	v_exp_f32_e32 v109, v109
	v_exp_f32_e32 v110, v110
	v_exp_f32_e32 v111, v111
	v_mfma_f32_32x32x16_bf16 v[112:127], v[182:185], v[140:143], v[112:127]
	v_cvt_pk_bf16_f32 v222, v96, v97
	v_cvt_pk_bf16_f32 v223, v98, v99
	v_cvt_pk_bf16_f32 v224, v100, v101
	v_cvt_pk_bf16_f32 v225, v102, v103
	v_exp_f32_e32 v80, v80
	v_exp_f32_e32 v81, v81
	v_mfma_f32_32x32x16_bf16 v[112:127], v[186:189], v[144:147], v[112:127]
	v_exp_f32_e32 v82, v82
	v_exp_f32_e32 v83, v83
	v_exp_f32_e32 v84, v84
	v_exp_f32_e32 v85, v85
	v_mfma_f32_32x32x16_bf16 v[112:127], v[190:193], v[148:151], v[112:127]
	v_exp_f32_e32 v86, v86
	v_exp_f32_e32 v87, v87
	v_cvt_pk_bf16_f32 v230, v104, v105
	v_cvt_pk_bf16_f32 v231, v106, v107
	v_cvt_pk_bf16_f32 v232, v108, v109
	v_cvt_pk_bf16_f32 v233, v110, v111
	v_mfma_f32_32x32x16_bf16 v[0:15], v[178:181], v[152:155], 0
	v_exp_f32_e32 v88, v88
	v_exp_f32_e32 v89, v89
	v_exp_f32_e32 v90, v90
	v_exp_f32_e32 v91, v91
	ds_read_b64_tr_b16 v[238:239], v221 offset:27648
	ds_read_b64_tr_b16 v[240:241], v221 offset:28800
	ds_read_b64_tr_b16 v[248:249], v221 offset:27712
	ds_read_b64_tr_b16 v[250:251], v221 offset:28864
	v_mfma_f32_32x32x16_bf16 v[0:15], v[182:185], v[156:159], v[0:15]
	v_exp_f32_e32 v92, v92
	v_exp_f32_e32 v93, v93
	v_exp_f32_e32 v94, v94
	v_exp_f32_e32 v95, v95
	v_mfma_f32_32x32x16_bf16 v[0:15], v[186:189], v[160:163], v[0:15]
	v_cvt_pk_bf16_f32 v226, v80, v81
	v_cvt_pk_bf16_f32 v227, v82, v83
	v_cvt_pk_bf16_f32 v228, v84, v85
	v_cvt_pk_bf16_f32 v229, v86, v87
	v_exp_f32_e32 v112, v112
	v_exp_f32_e32 v113, v113
	v_mfma_f32_32x32x16_bf16 v[0:15], v[190:193], v[164:167], v[0:15]
	v_exp_f32_e32 v114, v114
	v_exp_f32_e32 v115, v115
	v_exp_f32_e32 v116, v116
	v_exp_f32_e32 v117, v117
	ds_read_b64_tr_b16 v[194:195], v221 offset:29952
	ds_read_b64_tr_b16 v[196:197], v221 offset:31104
	ds_read_b64_tr_b16 v[210:211], v221 offset:30016
	ds_read_b64_tr_b16 v[212:213], v221 offset:31168
	s_waitcnt lgkmcnt(4)
	v_mfma_f32_32x32x16_bf16 v[48:63], v[222:225], v[238:241], v[48:63]
	v_exp_f32_e32 v118, v118
	v_exp_f32_e32 v119, v119
	v_exp_f32_e32 v120, v120
	v_exp_f32_e32 v121, v121
	v_mfma_f32_32x32x16_bf16 v[64:79], v[222:225], v[248:251], v[64:79]
	v_cvt_pk_bf16_f32 v234, v88, v89
	v_cvt_pk_bf16_f32 v235, v90, v91
	v_cvt_pk_bf16_f32 v236, v92, v93
	v_cvt_pk_bf16_f32 v237, v94, v95
	v_exp_f32_e32 v122, v122
	v_exp_f32_e32 v123, v123
	v_mfma_f32_32x32x16_bf16 v[16:31], v[226:229], v[238:241], v[16:31]
	v_exp_f32_e32 v124, v124
	v_exp_f32_e32 v125, v125
	v_exp_f32_e32 v126, v126
	v_exp_f32_e32 v127, v127
	v_mfma_f32_32x32x16_bf16 v[32:47], v[226:229], v[248:251], v[32:47]
	ds_read_b64_tr_b16 v[238:239], v221 offset:32256
	ds_read_b64_tr_b16 v[240:241], v221 offset:33408
	ds_read_b64_tr_b16 v[248:249], v221 offset:32320
	ds_read_b64_tr_b16 v[250:251], v221 offset:33472
	v_exp_f32_e32 v0, v0
	v_exp_f32_e32 v1, v1
	v_exp_f32_e32 v2, v2
	v_exp_f32_e32 v3, v3
	s_waitcnt lgkmcnt(4)
	v_mfma_f32_32x32x16_bf16 v[48:63], v[230:233], v[194:197], v[48:63]
	v_exp_f32_e32 v4, v4
	v_exp_f32_e32 v5, v5
	v_exp_f32_e32 v6, v6
	v_exp_f32_e32 v7, v7
	v_mfma_f32_32x32x16_bf16 v[64:79], v[230:233], v[210:213], v[64:79]
	v_cvt_pk_bf16_f32 v178, v112, v113
	v_cvt_pk_bf16_f32 v179, v114, v115
	v_cvt_pk_bf16_f32 v180, v116, v117
	v_cvt_pk_bf16_f32 v181, v118, v119
	v_exp_f32_e32 v8, v8
	v_exp_f32_e32 v9, v9
	v_mfma_f32_32x32x16_bf16 v[16:31], v[234:237], v[194:197], v[16:31]
	v_exp_f32_e32 v10, v10
	v_exp_f32_e32 v11, v11
	v_exp_f32_e32 v12, v12
	v_exp_f32_e32 v13, v13
	s_andn2_b64 vcc, exec, s[54:55]
	v_mfma_f32_32x32x16_bf16 v[32:47], v[234:237], v[210:213], v[32:47]
	ds_read_b64_tr_b16 v[194:195], v221 offset:34560
	ds_read_b64_tr_b16 v[196:197], v221 offset:35712
	ds_read_b64_tr_b16 v[210:211], v221 offset:34624
	ds_read_b64_tr_b16 v[212:213], v221 offset:35776
	v_exp_f32_e32 v14, v14
	v_exp_f32_e32 v15, v15
	v_cvt_pk_bf16_f32 v182, v0, v1
	v_cvt_pk_bf16_f32 v183, v2, v3
	v_cvt_pk_bf16_f32 v184, v4, v5
	v_cvt_pk_bf16_f32 v185, v6, v7
	v_cvt_pk_bf16_f32 v186, v120, v121
	v_cvt_pk_bf16_f32 v187, v122, v123
	v_cvt_pk_bf16_f32 v188, v124, v125
	v_cvt_pk_bf16_f32 v189, v126, v127
	v_cvt_pk_bf16_f32 v190, v8, v9
	v_cvt_pk_bf16_f32 v191, v10, v11
	v_cvt_pk_bf16_f32 v192, v12, v13
	v_cvt_pk_bf16_f32 v193, v14, v15
	s_cbranch_vccnz .Lr2n_nowriteB
	s_waitcnt vmcnt(0)
	ds_write_b128 v220, v[128:131] offset:0
	ds_write_b128 v220, v[132:135] offset:18432
; #define ALAS __attribute__((address_space(3)))
; #define AMFMA(a, b, c) __builtin_amdgcn_mfma_f32_32x32x16_bf16((a), (b), (c), 0, 0, 0)
; template <bool SUB> __device__ __forceinline__ void attn_unit_r2(const AU& u, ALAS unsigned char* lds, float mb2) {
;     ...
;                 oa0 = AMFMA(paa[ks], vf0, oa0); oa1 = AMFMA(paa[ks], vf1, oa1); ob0 = AMFMA(pab[ks], vf0, ob0); ob1 = AMFMA(pab[ks], vf1, ob1);
;             }
;         }
;         if (t + 1 < NT) { *(ALAS u32x4*)(lds + (cur ^ 1) * KBUF + kl0) = rk; *(ALAS u32x4*)(lds + (cur ^ 1) * VBUF + vl) = rv; }
;         __syncthreads();
;     }
;     la += __shfl_xor(la, 32); lb += __shfl_xor(lb, 32);
.Lr2n_nowriteB:
	s_cmp_lt_u32 s20, s7
	s_mov_b32 s21, s20
	s_waitcnt lgkmcnt(0)
	s_barrier
	s_cbranch_scc1 .Lr2n_topA
	v_mfma_f32_32x32x16_bf16 v[48:63], v[178:181], v[238:241], v[48:63]
	v_add_f32_e32 v172, v96, v172
	v_add_f32_e32 v173, v80, v173
	v_add_f32_e32 v172, v97, v172
	v_add_f32_e32 v173, v81, v173
	v_mfma_f32_32x32x16_bf16 v[64:79], v[178:181], v[248:251], v[64:79]
	v_add_f32_e32 v172, v98, v172
	v_add_f32_e32 v173, v82, v173
	v_add_f32_e32 v172, v99, v172
	v_add_f32_e32 v173, v83, v173
	v_mfma_f32_32x32x16_bf16 v[16:31], v[182:185], v[238:241], v[16:31]
	v_add_f32_e32 v172, v100, v172
	v_add_f32_e32 v173, v84, v173
	v_add_f32_e32 v172, v101, v172
	v_add_f32_e32 v173, v85, v173
	v_mfma_f32_32x32x16_bf16 v[32:47], v[182:185], v[248:251], v[32:47]
	v_add_f32_e32 v172, v102, v172
	v_add_f32_e32 v173, v86, v173
	v_add_f32_e32 v172, v103, v172
	v_add_f32_e32 v173, v87, v173
	v_mfma_f32_32x32x16_bf16 v[48:63], v[186:189], v[194:197], v[48:63]
	v_add_f32_e32 v172, v104, v172
	v_add_f32_e32 v173, v88, v173
	v_add_f32_e32 v172, v105, v172
	v_add_f32_e32 v173, v89, v173
	v_mfma_f32_32x32x16_bf16 v[64:79], v[186:189], v[210:213], v[64:79]
	v_add_f32_e32 v172, v106, v172
	v_add_f32_e32 v173, v90, v173
	v_add_f32_e32 v172, v107, v172
	v_add_f32_e32 v173, v91, v173
	v_mfma_f32_32x32x16_bf16 v[16:31], v[190:193], v[194:197], v[16:31]
	v_add_f32_e32 v172, v108, v172
	v_add_f32_e32 v173, v92, v173
	v_add_f32_e32 v172, v109, v172
	v_add_f32_e32 v173, v93, v173
	v_mfma_f32_32x32x16_bf16 v[32:47], v[190:193], v[210:213], v[32:47]
	v_add_f32_e32 v172, v110, v172
	v_add_f32_e32 v173, v94, v173
	v_add_f32_e32 v172, v111, v172
	v_add_f32_e32 v173, v95, v173
	v_add_f32_e32 v242, v112, v242
	v_add_f32_e32 v243, v0, v243
	v_add_f32_e32 v242, v113, v242
	v_add_f32_e32 v243, v1, v243
	v_add_f32_e32 v242, v114, v242
	v_add_f32_e32 v243, v2, v243
	v_add_f32_e32 v242, v115, v242
	v_add_f32_e32 v243, v3, v243
	v_add_f32_e32 v242, v116, v242
	v_add_f32_e32 v243, v4, v243
	v_add_f32_e32 v242, v117, v242
	v_add_f32_e32 v243, v5, v243
	v_add_f32_e32 v242, v118, v242
	v_add_f32_e32 v243, v6, v243
	v_add_f32_e32 v242, v119, v242
	v_add_f32_e32 v243, v7, v243
	v_add_f32_e32 v242, v120, v242
	v_add_f32_e32 v243, v8, v243
	v_add_f32_e32 v242, v121, v242
	v_add_f32_e32 v243, v9, v243
	v_add_f32_e32 v242, v122, v242
	v_add_f32_e32 v243, v10, v243
	v_add_f32_e32 v242, v123, v242
	v_add_f32_e32 v243, v11, v243
	v_add_f32_e32 v242, v124, v242
	v_add_f32_e32 v243, v12, v243
	v_add_f32_e32 v242, v125, v242
	v_add_f32_e32 v243, v13, v243
	v_add_f32_e32 v242, v126, v242
	v_add_f32_e32 v243, v14, v243
	v_add_f32_e32 v242, v127, v242
	v_add_f32_e32 v243, v15, v243
	v_add_f32_e32 v172, v172, v242
	v_add_f32_e32 v173, v173, v243
	v_xor_b32_e32 v0, 0x80000000, v219
	v_mov_b32_e32 v1, v0
	v_mov_b32_e32 v2, v0
	v_mov_b32_e32 v3, v0
	v_mov_b32_e32 v4, v0
	v_mov_b32_e32 v5, v0
	v_mov_b32_e32 v6, v0
	v_mov_b32_e32 v7, v0
	v_mov_b32_e32 v8, v0
	v_mov_b32_e32 v9, v0
	v_mov_b32_e32 v10, v0
	v_mov_b32_e32 v11, v0
	v_mov_b32_e32 v12, v0
	v_mov_b32_e32 v13, v0
	v_mov_b32_e32 v14, v0
	v_mov_b32_e32 v15, v0

; #define ALAS __attribute__((address_space(3)))
; #define AMFMA(a, b, c) __builtin_amdgcn_mfma_f32_32x32x16_bf16((a), (b), (c), 0, 0, 0)
; template <bool SUB> __device__ __forceinline__ void attn_unit_r2b(const AU& u, ALAS unsigned char* lds, float mb2) {
;     ...
;         if (t + 1 < NT) { const size_t ro = (size_t)(t + 1) * 64; rk0 = *(const u32x4*)(kg0 + ro * u.krs); if (k2) rk1 = *(const u32x4*)(kg1 + ro * u.krs); rv = *(const u32x4*)(vg + ro * u.vrs); }
;         {
;             const ALAS unsigned char* kb = lds + cur * KBUF + r * KP + h * 16;
;             const ALAS unsigned char* vb = lds + V_OFF + cur * VBUF + (4 * h + ((lane & 15) >> 2)) * VP + ((lane >> 4) & 1) * 32 + (lane & 3) * 8;
;             bf16x8 paa[4], pab[4];
;             f32x16 Sa0, Sa1, Sb0, Sb1;
; #pragma unroll
;             for (int i = 0; i < 16; ++i) { Sa0[i] = 0.f; Sa1[i] = 0.f; Sb0[i] = 0.f; Sb1[i] = 0.f; }
; #pragma unroll
;             for (int d0 = 0; d0 < 6; ++d0) {
;                 const bf16x8 k0 = *(const ALAS bf16x8*)(kb + d0 * 32), k1 = *(const ALAS bf16x8*)(kb + 32 * KP + d0 * 32); const bf16x8 qbv = *(const ALAS bf16x8*)(qbl + d0 * 1024);
;                 Sa0 = AMFMA(k0, qa[d0], Sa0); Sa1 = AMFMA(k1, qa[d0], Sa1); Sb0 = AMFMA(k0, qbv, Sb0); Sb1 = AMFMA(k1, qbv, Sb1);
;                 if (d0 & 1) __builtin_amdgcn_sched_barrier(0);
;             }
;     ...
;             R2B_SOFT(Sa0, Sa1, paa, la);
;             __builtin_amdgcn_sched_barrier(0);
;             R2B_SOFT(Sb0, Sb1, pab, lb);
.Lr2b_topA:
	global_load_dwordx4 v[152:155], v[172:173], off
	s_and_saveexec_b64 s[58:59], s[40:41]
	s_cbranch_execz .Lr2b_nok2A
	global_load_dwordx4 v[156:159], v[174:175], off
.Lr2b_nok2A:
	s_or_b64 exec, exec, s[58:59]
	global_load_dwordx4 v[160:163], v[166:167], off
	ds_read_b128 v[218:221], v168 offset:0
	ds_read_b128 v[222:225], v168 offset:32
	ds_read_b128 v[226:229], v168 offset:64
	ds_read_b128 v[230:233], v168 offset:96
	ds_read_b128 v[234:237], v168 offset:128
	ds_read_b128 v[238:241], v168 offset:160
	ds_read_b128 v[176:179], v193 offset:45056
	ds_read_b128 v[180:183], v193 offset:46080
	ds_read_b128 v[184:187], v193 offset:47104
	ds_read_b128 v[248:251], v193 offset:48128
	ds_read_b128 v[244:247], v193 offset:49152
	s_waitcnt lgkmcnt(5)
	v_mfma_f32_32x32x16_bf16 v[96:111], v[218:221], v[128:131], 0
	v_lshl_add_u64 v[166:167], v[166:167], 0, s[8:9]
	v_add_f32_e32 v242, v112, v242
	v_add_f32_e32 v243, v80, v243
	v_add_f32_e32 v242, v113, v242
	v_add_f32_e32 v243, v81, v243
	v_mfma_f32_32x32x16_bf16 v[96:111], v[222:225], v[132:135], v[96:111]
	v_lshl_add_u64 v[172:173], v[172:173], 0, s[12:13]
	v_add_f32_e32 v242, v114, v242
	v_add_f32_e32 v243, v82, v243
	v_add_f32_e32 v242, v115, v242
	v_add_f32_e32 v243, v83, v243
	v_mfma_f32_32x32x16_bf16 v[96:111], v[226:229], v[136:139], v[96:111]
	v_lshl_add_u64 v[174:175], v[174:175], 0, s[12:13]
	v_add_f32_e32 v242, v116, v242
	v_add_f32_e32 v243, v84, v243
	v_add_f32_e32 v242, v117, v242
	v_add_f32_e32 v243, v85, v243
	v_mfma_f32_32x32x16_bf16 v[96:111], v[230:233], v[140:143], v[96:111]
	v_add_f32_e32 v242, v118, v242
	v_add_f32_e32 v243, v86, v243
	v_add_f32_e32 v242, v119, v242
	v_add_f32_e32 v243, v87, v243
	v_add_f32_e32 v242, v120, v242
	v_mfma_f32_32x32x16_bf16 v[96:111], v[234:237], v[144:147], v[96:111]
	v_add_f32_e32 v243, v88, v243
	v_add_f32_e32 v242, v121, v242
	v_add_f32_e32 v243, v89, v243
	v_add_f32_e32 v242, v122, v242
	v_add_f32_e32 v243, v90, v243
	v_add_f32_e32 v242, v123, v242
	v_mfma_f32_32x32x16_bf16 v[96:111], v[238:241], v[148:151], v[96:111]
	v_add_f32_e32 v243, v91, v243
	v_add_f32_e32 v242, v124, v242
	v_add_f32_e32 v243, v92, v243
	v_add_f32_e32 v242, v125, v242
	v_add_f32_e32 v243, v93, v243
	v_add_f32_e32 v242, v126, v242
	s_waitcnt lgkmcnt(0)
	v_mfma_f32_32x32x16_bf16 v[64:79], v[218:221], v[176:179], 0
	ds_read_b128 v[176:179], v193 offset:50176
	ds_read_b128 v[218:221], v168 offset:6656
	v_add_f32_e32 v243, v94, v243
	v_add_f32_e32 v242, v127, v242
	v_add_f32_e32 v243, v95, v243
	v_mfma_f32_32x32x16_bf16 v[64:79], v[222:225], v[180:183], v[64:79]
	ds_read_b128 v[222:225], v168 offset:6688
	v_exp_f32_e32 v96, v96
	v_exp_f32_e32 v97, v97
	v_mfma_f32_32x32x16_bf16 v[64:79], v[226:229], v[184:187], v[64:79]
	ds_read_b128 v[226:229], v168 offset:6720
	v_exp_f32_e32 v98, v98
	v_exp_f32_e32 v99, v99
	v_mfma_f32_32x32x16_bf16 v[64:79], v[230:233], v[248:251], v[64:79]
	ds_read_b128 v[230:233], v168 offset:6752
	v_exp_f32_e32 v100, v100
	v_exp_f32_e32 v101, v101
	v_mfma_f32_32x32x16_bf16 v[64:79], v[234:237], v[244:247], v[64:79]
	ds_read_b128 v[234:237], v168 offset:6784
	v_exp_f32_e32 v102, v102
	v_exp_f32_e32 v103, v103
	s_waitcnt lgkmcnt(5)
	v_mfma_f32_32x32x16_bf16 v[64:79], v[238:241], v[176:179], v[64:79]
	ds_read_b128 v[238:241], v168 offset:6816
	ds_read_b128 v[176:179], v193 offset:45056
	v_exp_f32_e32 v104, v104
	v_exp_f32_e32 v105, v105
	v_exp_f32_e32 v106, v106
	v_exp_f32_e32 v107, v107
	s_waitcnt lgkmcnt(1)
	v_mfma_f32_32x32x16_bf16 v[112:127], v[218:221], v[128:131], 0
	v_exp_f32_e32 v108, v108
	v_exp_f32_e32 v109, v109
	v_exp_f32_e32 v110, v110
	v_exp_f32_e32 v111, v111
	v_mfma_f32_32x32x16_bf16 v[112:127], v[222:225], v[132:135], v[112:127]
	v_exp_f32_e32 v64, v64
	v_exp_f32_e32 v65, v65
	v_exp_f32_e32 v66, v66
	v_mfma_f32_32x32x16_bf16 v[112:127], v[226:229], v[136:139], v[112:127]
	v_exp_f32_e32 v67, v67
	v_exp_f32_e32 v68, v68
	v_exp_f32_e32 v69, v69
	v_mfma_f32_32x32x16_bf16 v[112:127], v[230:233], v[140:143], v[112:127]
	v_exp_f32_e32 v70, v70
	v_exp_f32_e32 v71, v71
	v_exp_f32_e32 v72, v72
	v_mfma_f32_32x32x16_bf16 v[112:127], v[234:237], v[144:147], v[112:127]
	v_exp_f32_e32 v73, v73
	v_exp_f32_e32 v74, v74
	v_exp_f32_e32 v75, v75
	v_mfma_f32_32x32x16_bf16 v[112:127], v[238:241], v[148:151], v[112:127]
	v_exp_f32_e32 v76, v76
	v_exp_f32_e32 v77, v77
	v_exp_f32_e32 v78, v78
	v_exp_f32_e32 v79, v79
	s_waitcnt lgkmcnt(0)
	v_mfma_f32_32x32x16_bf16 v[80:95], v[218:221], v[176:179], 0
	ds_read_b128 v[176:179], v193 offset:50176
	v_cvt_pk_bf16_f32 v218, v96, v97
	v_cvt_pk_bf16_f32 v219, v98, v99
	v_cvt_pk_bf16_f32 v220, v100, v101
	v_cvt_pk_bf16_f32 v221, v102, v103
	v_mfma_f32_32x32x16_bf16 v[80:95], v[222:225], v[180:183], v[80:95]
	v_cvt_pk_bf16_f32 v222, v64, v65
	v_cvt_pk_bf16_f32 v223, v66, v67
	v_cvt_pk_bf16_f32 v224, v68, v69
	v_cvt_pk_bf16_f32 v225, v70, v71
	v_exp_f32_e32 v112, v112
	v_exp_f32_e32 v113, v113
	v_mfma_f32_32x32x16_bf16 v[80:95], v[226:229], v[184:187], v[80:95]
	v_cvt_pk_bf16_f32 v226, v104, v105
	v_cvt_pk_bf16_f32 v227, v106, v107
	v_cvt_pk_bf16_f32 v228, v108, v109
	v_cvt_pk_bf16_f32 v229, v110, v111
	v_exp_f32_e32 v114, v114
	v_exp_f32_e32 v115, v115
	ds_read_b64_tr_b16 v[184:185], v197 offset:26624
	ds_read_b64_tr_b16 v[186:187], v197 offset:27776
	v_mfma_f32_32x32x16_bf16 v[80:95], v[230:233], v[248:251], v[80:95]
	v_cvt_pk_bf16_f32 v230, v72, v73
	v_cvt_pk_bf16_f32 v231, v74, v75
	v_cvt_pk_bf16_f32 v232, v76, v77
	v_cvt_pk_bf16_f32 v233, v78, v79
	v_exp_f32_e32 v116, v116
	v_exp_f32_e32 v117, v117
	ds_read_b64_tr_b16 v[248:249], v197 offset:26688
	ds_read_b64_tr_b16 v[250:251], v197 offset:27840
	v_mfma_f32_32x32x16_bf16 v[80:95], v[234:237], v[244:247], v[80:95]
	v_exp_f32_e32 v118, v118
	v_exp_f32_e32 v119, v119
	v_exp_f32_e32 v120, v120
	v_exp_f32_e32 v121, v121
	ds_read_b64_tr_b16 v[244:245], v197 offset:28928
	ds_read_b64_tr_b16 v[246:247], v197 offset:30080
	s_waitcnt lgkmcnt(6)
; #define ALAS __attribute__((address_space(3)))
; __device__ __forceinline__ s16x4 vtr(const ALAS unsigned char* p) { return __builtin_bit_cast(s16x4, __builtin_amdgcn_ds_read_tr16_b64_v4i16((ALAS s16x4*)p)); }
; #define AMFMA(a, b, c) __builtin_amdgcn_mfma_f32_32x32x16_bf16((a), (b), (c), 0, 0, 0)
; template <bool SUB> __device__ __forceinline__ void attn_unit_r2b(const AU& u, ALAS unsigned char* lds, float mb2) {
;     ...
;             R2B_SOFT(Sb0, Sb1, pab, lb);
;     ...
; #pragma unroll
;             for (int ks = 0; ks < 4; ++ks) {
;                 const s16x4 lo0 = vtr(vb + ks * 16 * VP), hi0 = vtr(vb + (ks * 16 + 8) * VP), lo1 = vtr(vb + ks * 16 * VP + 64), hi1 = vtr(vb + (ks * 16 + 8) * VP + 64);
;                 const bf16x8 vf0 = __builtin_shufflevector(lo0, hi0, 0, 1, 2, 3, 4, 5, 6, 7), vf1 = __builtin_shufflevector(lo1, hi1, 0, 1, 2, 3, 4, 5, 6, 7);
;                 oa0 = AMFMA(paa[ks], vf0, oa0); oa1 = AMFMA(paa[ks], vf1, oa1); ob0 = AMFMA(pab[ks], vf0, ob0); ob1 = AMFMA(pab[ks], vf1, ob1);
;             }
;         }
;         if (t + 1 < NT) { *(ALAS u32x4*)(lds + (cur ^ 1) * KBUF + kl0) = rk0; if (k2) *(ALAS u32x4*)(lds + (cur ^ 1) * KBUF + kl1) = rk1; *(ALAS u32x4*)(lds + (cur ^ 1) * VBUF + vl) = rv; }
;         __syncthreads();
	v_mfma_f32_32x32x16_bf16 v[80:95], v[238:241], v[176:179], v[80:95]
	v_exp_f32_e32 v122, v122
	v_exp_f32_e32 v123, v123
	v_exp_f32_e32 v124, v124
	v_exp_f32_e32 v125, v125
	s_waitcnt lgkmcnt(2)
	v_mfma_f32_32x32x16_bf16 v[32:47], v[218:221], v[184:187], v[32:47]
	v_exp_f32_e32 v126, v126
	v_exp_f32_e32 v127, v127
	v_cvt_pk_bf16_f32 v234, v112, v113
	v_cvt_pk_bf16_f32 v235, v114, v115
	v_cvt_pk_bf16_f32 v236, v116, v117
	v_cvt_pk_bf16_f32 v237, v118, v119
	v_mfma_f32_32x32x16_bf16 v[48:63], v[218:221], v[248:251], v[48:63]
	v_exp_f32_e32 v80, v80
	v_exp_f32_e32 v81, v81
	v_exp_f32_e32 v82, v82
	v_exp_f32_e32 v83, v83
	v_mfma_f32_32x32x16_bf16 v[0:15], v[222:225], v[184:187], v[0:15]
	ds_read_b64_tr_b16 v[184:185], v197 offset:28992
	ds_read_b64_tr_b16 v[186:187], v197 offset:30144
	v_exp_f32_e32 v84, v84
	v_exp_f32_e32 v85, v85
	v_exp_f32_e32 v86, v86
	v_exp_f32_e32 v87, v87
	v_mfma_f32_32x32x16_bf16 v[16:31], v[222:225], v[248:251], v[16:31]
	ds_read_b64_tr_b16 v[248:249], v197 offset:31232
	ds_read_b64_tr_b16 v[250:251], v197 offset:32384
	v_exp_f32_e32 v88, v88
	v_exp_f32_e32 v89, v89
	v_exp_f32_e32 v90, v90
	v_exp_f32_e32 v91, v91
	s_waitcnt lgkmcnt(2)
	v_mfma_f32_32x32x16_bf16 v[32:47], v[226:229], v[244:247], v[32:47]
	v_exp_f32_e32 v92, v92
	v_exp_f32_e32 v93, v93
	v_exp_f32_e32 v94, v94
	v_exp_f32_e32 v95, v95
	v_mfma_f32_32x32x16_bf16 v[48:63], v[226:229], v[184:187], v[48:63]
	v_cvt_pk_bf16_f32 v176, v120, v121
	v_cvt_pk_bf16_f32 v177, v122, v123
	v_cvt_pk_bf16_f32 v178, v124, v125
	v_cvt_pk_bf16_f32 v179, v126, v127
	v_cvt_pk_bf16_f32 v238, v80, v81
	v_cvt_pk_bf16_f32 v239, v82, v83
	v_cvt_pk_bf16_f32 v240, v84, v85
	v_cvt_pk_bf16_f32 v241, v86, v87
	v_mfma_f32_32x32x16_bf16 v[0:15], v[230:233], v[244:247], v[0:15]
	ds_read_b64_tr_b16 v[244:245], v197 offset:31296
	ds_read_b64_tr_b16 v[246:247], v197 offset:32448
	v_cvt_pk_bf16_f32 v180, v88, v89
	v_cvt_pk_bf16_f32 v181, v90, v91
	v_cvt_pk_bf16_f32 v182, v92, v93
	v_cvt_pk_bf16_f32 v183, v94, v95
	v_add_f32_e32 v164, v96, v164
	v_add_f32_e32 v165, v64, v165
	v_add_f32_e32 v164, v97, v164
	v_mfma_f32_32x32x16_bf16 v[16:31], v[230:233], v[184:187], v[16:31]
	ds_read_b64_tr_b16 v[184:185], v197 offset:33536
	ds_read_b64_tr_b16 v[186:187], v197 offset:34688
	v_add_f32_e32 v165, v65, v165
	v_add_f32_e32 v164, v98, v164
	v_add_f32_e32 v165, v66, v165
	v_add_f32_e32 v164, v99, v164
	v_add_f32_e32 v165, v67, v165
	s_waitcnt lgkmcnt(2)
	v_mfma_f32_32x32x16_bf16 v[32:47], v[234:237], v[248:251], v[32:47]
	v_add_f32_e32 v164, v100, v164
	v_add_f32_e32 v165, v68, v165
	v_add_f32_e32 v164, v101, v164
	v_add_f32_e32 v165, v69, v165
	v_add_f32_e32 v164, v102, v164
	v_add_f32_e32 v165, v70, v165
	v_mfma_f32_32x32x16_bf16 v[48:63], v[234:237], v[244:247], v[48:63]
	v_add_f32_e32 v164, v103, v164
	v_add_f32_e32 v165, v71, v165
	v_add_f32_e32 v164, v104, v164
	v_add_f32_e32 v165, v72, v165
	v_add_f32_e32 v164, v105, v164
	v_add_f32_e32 v165, v73, v165
	v_mfma_f32_32x32x16_bf16 v[0:15], v[238:241], v[248:251], v[0:15]
	ds_read_b64_tr_b16 v[248:249], v197 offset:33600
	ds_read_b64_tr_b16 v[250:251], v197 offset:34752
	v_add_f32_e32 v164, v106, v164
	v_add_f32_e32 v165, v74, v165
	v_add_f32_e32 v164, v107, v164
	v_add_f32_e32 v165, v75, v165
	v_add_f32_e32 v164, v108, v164
	v_mfma_f32_32x32x16_bf16 v[16:31], v[238:241], v[244:247], v[16:31]
	v_add_f32_e32 v165, v76, v165
	v_add_f32_e32 v164, v109, v164
	v_add_f32_e32 v165, v77, v165
	v_add_f32_e32 v164, v110, v164
	v_add_f32_e32 v165, v78, v165
	v_add_f32_e32 v164, v111, v164
	s_waitcnt lgkmcnt(0)
	v_mfma_f32_32x32x16_bf16 v[32:47], v[176:179], v[184:187], v[32:47]
	v_add_f32_e32 v165, v79, v165
	v_mfma_f32_32x32x16_bf16 v[48:63], v[176:179], v[248:251], v[48:63]
	s_waitcnt vmcnt(0)
	ds_write_b128 v194, v[152:155] offset:13312
	s_and_saveexec_b64 s[58:59], s[40:41]
	s_cbranch_execz .Lr2b_nok2wA
	ds_write_b128 v195, v[156:159] offset:13312
.Lr2b_nok2wA:
	s_or_b64 exec, exec, s[58:59]
	ds_write_b128 v196, v[160:163] offset:35840
	v_mfma_f32_32x32x16_bf16 v[0:15], v[180:183], v[184:187], v[0:15]
	v_mfma_f32_32x32x16_bf16 v[16:31], v[180:183], v[248:251], v[16:31]
	s_waitcnt lgkmcnt(0)
	s_barrier
.Lr2b_topB:
	s_add_i32 s61, s62, 2
	s_cmp_lt_u32 s61, s28
	s_cselect_b64 s[56:57], -1, 0
	s_cbranch_scc0 .Lr2b_noloadB
	global_load_dwordx4 v[152:155], v[172:173], off
	s_and_saveexec_b64 s[58:59], s[40:41]
	s_cbranch_execz .Lr2b_nok2B
	global_load_dwordx4 v[156:159], v[174:175], off

; #define ALAS __attribute__((address_space(3)))
; #define AMFMA(a, b, c) __builtin_amdgcn_mfma_f32_32x32x16_bf16((a), (b), (c), 0, 0, 0)
; template <bool SUB> __device__ __forceinline__ void attn_unit_r2b(const AU& u, ALAS unsigned char* lds, float mb2) {
;     ...
;         if (t + 1 < NT) { const size_t ro = (size_t)(t + 1) * 64; rk0 = *(const u32x4*)(kg0 + ro * u.krs); if (k2) rk1 = *(const u32x4*)(kg1 + ro * u.krs); rv = *(const u32x4*)(vg + ro * u.vrs); }
;         {
;             const ALAS unsigned char* kb = lds + cur * KBUF + r * KP + h * 16;
;             const ALAS unsigned char* vb = lds + V_OFF + cur * VBUF + (4 * h + ((lane & 15) >> 2)) * VP + ((lane >> 4) & 1) * 32 + (lane & 3) * 8;
;             bf16x8 paa[4], pab[4];
;             f32x16 Sa0, Sa1, Sb0, Sb1;
; #pragma unroll
;             for (int i = 0; i < 16; ++i) { Sa0[i] = 0.f; Sa1[i] = 0.f; Sb0[i] = 0.f; Sb1[i] = 0.f; }
; #pragma unroll
;             for (int d0 = 0; d0 < 6; ++d0) {
;                 const bf16x8 k0 = *(const ALAS bf16x8*)(kb + d0 * 32), k1 = *(const ALAS bf16x8*)(kb + 32 * KP + d0 * 32); const bf16x8 qbv = *(const ALAS bf16x8*)(qbl + d0 * 1024);
;                 Sa0 = AMFMA(k0, qa[d0], Sa0); Sa1 = AMFMA(k1, qa[d0], Sa1); Sb0 = AMFMA(k0, qbv, Sb0); Sb1 = AMFMA(k1, qbv, Sb1);
;                 if (d0 & 1) __builtin_amdgcn_sched_barrier(0);
;             }
;     ...
;             R2B_SOFT(Sa0, Sa1, paa, la);
;             __builtin_amdgcn_sched_barrier(0);
;             R2B_SOFT(Sb0, Sb1, pab, lb);
.Lr2b_noloadB:
	ds_read_b128 v[218:221], v168 offset:13312
	ds_read_b128 v[222:225], v168 offset:13344
	ds_read_b128 v[226:229], v168 offset:13376
	ds_read_b128 v[230:233], v168 offset:13408
	ds_read_b128 v[234:237], v168 offset:13440
	ds_read_b128 v[238:241], v168 offset:13472
	ds_read_b128 v[176:179], v193 offset:45056
	ds_read_b128 v[180:183], v193 offset:46080
	ds_read_b128 v[184:187], v193 offset:47104
	ds_read_b128 v[248:251], v193 offset:48128
	ds_read_b128 v[244:247], v193 offset:49152
	s_waitcnt lgkmcnt(5)
	v_mfma_f32_32x32x16_bf16 v[96:111], v[218:221], v[128:131], 0
	v_lshl_add_u64 v[166:167], v[166:167], 0, s[8:9]
	v_add_f32_e32 v242, v112, v242
	v_add_f32_e32 v243, v80, v243
	v_add_f32_e32 v242, v113, v242
	v_add_f32_e32 v243, v81, v243
	v_mfma_f32_32x32x16_bf16 v[96:111], v[222:225], v[132:135], v[96:111]
	v_lshl_add_u64 v[172:173], v[172:173], 0, s[12:13]
	v_add_f32_e32 v242, v114, v242
	v_add_f32_e32 v243, v82, v243
	v_add_f32_e32 v242, v115, v242
	v_add_f32_e32 v243, v83, v243
	v_mfma_f32_32x32x16_bf16 v[96:111], v[226:229], v[136:139], v[96:111]
	v_lshl_add_u64 v[174:175], v[174:175], 0, s[12:13]
	v_add_f32_e32 v242, v116, v242
	v_add_f32_e32 v243, v84, v243
	v_add_f32_e32 v242, v117, v242
	v_add_f32_e32 v243, v85, v243
	v_mfma_f32_32x32x16_bf16 v[96:111], v[230:233], v[140:143], v[96:111]
	v_add_f32_e32 v242, v118, v242
	v_add_f32_e32 v243, v86, v243
	v_add_f32_e32 v242, v119, v242
	v_add_f32_e32 v243, v87, v243
	v_add_f32_e32 v242, v120, v242
	v_mfma_f32_32x32x16_bf16 v[96:111], v[234:237], v[144:147], v[96:111]
	v_add_f32_e32 v243, v88, v243
	v_add_f32_e32 v242, v121, v242
	v_add_f32_e32 v243, v89, v243
	v_add_f32_e32 v242, v122, v242
	v_add_f32_e32 v243, v90, v243
	v_add_f32_e32 v242, v123, v242
	v_mfma_f32_32x32x16_bf16 v[96:111], v[238:241], v[148:151], v[96:111]
	v_add_f32_e32 v243, v91, v243
	v_add_f32_e32 v242, v124, v242
	v_add_f32_e32 v243, v92, v243
	v_add_f32_e32 v242, v125, v242
	v_add_f32_e32 v243, v93, v243
	v_add_f32_e32 v242, v126, v242
	s_waitcnt lgkmcnt(0)
	v_mfma_f32_32x32x16_bf16 v[64:79], v[218:221], v[176:179], 0
	ds_read_b128 v[176:179], v193 offset:50176
	ds_read_b128 v[218:221], v168 offset:19968
	v_add_f32_e32 v243, v94, v243
	v_add_f32_e32 v242, v127, v242
	v_add_f32_e32 v243, v95, v243
	v_mfma_f32_32x32x16_bf16 v[64:79], v[222:225], v[180:183], v[64:79]
	ds_read_b128 v[222:225], v168 offset:20000
	v_exp_f32_e32 v96, v96
	v_exp_f32_e32 v97, v97
	v_mfma_f32_32x32x16_bf16 v[64:79], v[226:229], v[184:187], v[64:79]
	ds_read_b128 v[226:229], v168 offset:20032
	v_exp_f32_e32 v98, v98
	v_exp_f32_e32 v99, v99
	v_mfma_f32_32x32x16_bf16 v[64:79], v[230:233], v[248:251], v[64:79]
	ds_read_b128 v[230:233], v168 offset:20064
	v_exp_f32_e32 v100, v100
	v_exp_f32_e32 v101, v101
	v_mfma_f32_32x32x16_bf16 v[64:79], v[234:237], v[244:247], v[64:79]
	ds_read_b128 v[234:237], v168 offset:20096
	v_exp_f32_e32 v102, v102
	v_exp_f32_e32 v103, v103
	s_waitcnt lgkmcnt(5)
	v_mfma_f32_32x32x16_bf16 v[64:79], v[238:241], v[176:179], v[64:79]
	ds_read_b128 v[238:241], v168 offset:20128
	ds_read_b128 v[176:179], v193 offset:45056
	v_exp_f32_e32 v104, v104
	v_exp_f32_e32 v105, v105
	v_exp_f32_e32 v106, v106
	v_exp_f32_e32 v107, v107
	s_waitcnt lgkmcnt(1)
	v_mfma_f32_32x32x16_bf16 v[112:127], v[218:221], v[128:131], 0
	v_exp_f32_e32 v108, v108
	v_exp_f32_e32 v109, v109
	v_exp_f32_e32 v110, v110
	v_exp_f32_e32 v111, v111
	v_mfma_f32_32x32x16_bf16 v[112:127], v[222:225], v[132:135], v[112:127]
	v_exp_f32_e32 v64, v64
	v_exp_f32_e32 v65, v65
	v_exp_f32_e32 v66, v66
	v_mfma_f32_32x32x16_bf16 v[112:127], v[226:229], v[136:139], v[112:127]
	v_exp_f32_e32 v67, v67
	v_exp_f32_e32 v68, v68
	v_exp_f32_e32 v69, v69
	v_mfma_f32_32x32x16_bf16 v[112:127], v[230:233], v[140:143], v[112:127]
	v_exp_f32_e32 v70, v70
	v_exp_f32_e32 v71, v71
	v_exp_f32_e32 v72, v72
	v_mfma_f32_32x32x16_bf16 v[112:127], v[234:237], v[144:147], v[112:127]
	v_exp_f32_e32 v73, v73
	v_exp_f32_e32 v74, v74
	v_exp_f32_e32 v75, v75
	v_mfma_f32_32x32x16_bf16 v[112:127], v[238:241], v[148:151], v[112:127]
	v_exp_f32_e32 v76, v76
	v_exp_f32_e32 v77, v77
	v_exp_f32_e32 v78, v78
	v_exp_f32_e32 v79, v79
	s_waitcnt lgkmcnt(0)
	v_mfma_f32_32x32x16_bf16 v[80:95], v[218:221], v[176:179], 0
	ds_read_b128 v[176:179], v193 offset:50176
	v_cvt_pk_bf16_f32 v218, v96, v97
	v_cvt_pk_bf16_f32 v219, v98, v99
	v_cvt_pk_bf16_f32 v220, v100, v101
	v_cvt_pk_bf16_f32 v221, v102, v103
	v_mfma_f32_32x32x16_bf16 v[80:95], v[222:225], v[180:183], v[80:95]
	v_cvt_pk_bf16_f32 v222, v64, v65
	v_cvt_pk_bf16_f32 v223, v66, v67
	v_cvt_pk_bf16_f32 v224, v68, v69
	v_cvt_pk_bf16_f32 v225, v70, v71
	v_exp_f32_e32 v112, v112
	v_exp_f32_e32 v113, v113
	v_mfma_f32_32x32x16_bf16 v[80:95], v[226:229], v[184:187], v[80:95]
	v_cvt_pk_bf16_f32 v226, v104, v105
	v_cvt_pk_bf16_f32 v227, v106, v107
	v_cvt_pk_bf16_f32 v228, v108, v109
	v_cvt_pk_bf16_f32 v229, v110, v111
	v_exp_f32_e32 v114, v114
	v_exp_f32_e32 v115, v115
	ds_read_b64_tr_b16 v[184:185], v197 offset:35840
	ds_read_b64_tr_b16 v[186:187], v197 offset:36992
	v_mfma_f32_32x32x16_bf16 v[80:95], v[230:233], v[248:251], v[80:95]
	v_cvt_pk_bf16_f32 v230, v72, v73
	v_cvt_pk_bf16_f32 v231, v74, v75
	v_cvt_pk_bf16_f32 v232, v76, v77
	v_cvt_pk_bf16_f32 v233, v78, v79
	v_exp_f32_e32 v116, v116
	v_exp_f32_e32 v117, v117
	ds_read_b64_tr_b16 v[248:249], v197 offset:35904
	ds_read_b64_tr_b16 v[250:251], v197 offset:37056
	v_mfma_f32_32x32x16_bf16 v[80:95], v[234:237], v[244:247], v[80:95]
	v_exp_f32_e32 v118, v118
	v_exp_f32_e32 v119, v119
	v_exp_f32_e32 v120, v120
	v_exp_f32_e32 v121, v121
	ds_read_b64_tr_b16 v[244:245], v197 offset:38144
	ds_read_b64_tr_b16 v[246:247], v197 offset:39296
	s_waitcnt lgkmcnt(6)
; #define ALAS __attribute__((address_space(3)))
; __device__ __forceinline__ s16x4 vtr(const ALAS unsigned char* p) { return __builtin_bit_cast(s16x4, __builtin_amdgcn_ds_read_tr16_b64_v4i16((ALAS s16x4*)p)); }
; #define AMFMA(a, b, c) __builtin_amdgcn_mfma_f32_32x32x16_bf16((a), (b), (c), 0, 0, 0)
; template <bool SUB> __device__ __forceinline__ void attn_unit_r2b(const AU& u, ALAS unsigned char* lds, float mb2) {
;     ...
;             for (int ks = 0; ks < 4; ++ks) {
;                 const s16x4 lo0 = vtr(vb + ks * 16 * VP), hi0 = vtr(vb + (ks * 16 + 8) * VP), lo1 = vtr(vb + ks * 16 * VP + 64), hi1 = vtr(vb + (ks * 16 + 8) * VP + 64);
;                 const bf16x8 vf0 = __builtin_shufflevector(lo0, hi0, 0, 1, 2, 3, 4, 5, 6, 7), vf1 = __builtin_shufflevector(lo1, hi1, 0, 1, 2, 3, 4, 5, 6, 7);
;                 oa0 = AMFMA(paa[ks], vf0, oa0); oa1 = AMFMA(paa[ks], vf1, oa1); ob0 = AMFMA(pab[ks], vf0, ob0); ob1 = AMFMA(pab[ks], vf1, ob1);
;             }
;         }
;         if (t + 1 < NT) { *(ALAS u32x4*)(lds + (cur ^ 1) * KBUF + kl0) = rk0; if (k2) *(ALAS u32x4*)(lds + (cur ^ 1) * KBUF + kl1) = rk1; *(ALAS u32x4*)(lds + (cur ^ 1) * VBUF + vl) = rv; }
;         __syncthreads();
;     }
;     la += __shfl_xor(la, 32); lb += __shfl_xor(lb, 32);
	v_mfma_f32_32x32x16_bf16 v[80:95], v[238:241], v[176:179], v[80:95]
	v_exp_f32_e32 v122, v122
	v_exp_f32_e32 v123, v123
	v_exp_f32_e32 v124, v124
	v_exp_f32_e32 v125, v125
	s_waitcnt lgkmcnt(2)
	v_mfma_f32_32x32x16_bf16 v[32:47], v[218:221], v[184:187], v[32:47]
	v_exp_f32_e32 v126, v126
	v_exp_f32_e32 v127, v127
	v_cvt_pk_bf16_f32 v234, v112, v113
	v_cvt_pk_bf16_f32 v235, v114, v115
	v_cvt_pk_bf16_f32 v236, v116, v117
	v_cvt_pk_bf16_f32 v237, v118, v119
	v_mfma_f32_32x32x16_bf16 v[48:63], v[218:221], v[248:251], v[48:63]
	v_exp_f32_e32 v80, v80
	v_exp_f32_e32 v81, v81
	v_exp_f32_e32 v82, v82
	v_exp_f32_e32 v83, v83
	v_mfma_f32_32x32x16_bf16 v[0:15], v[222:225], v[184:187], v[0:15]
	ds_read_b64_tr_b16 v[184:185], v197 offset:38208
	ds_read_b64_tr_b16 v[186:187], v197 offset:39360
	v_exp_f32_e32 v84, v84
	v_exp_f32_e32 v85, v85
	v_exp_f32_e32 v86, v86
	v_exp_f32_e32 v87, v87
	v_mfma_f32_32x32x16_bf16 v[16:31], v[222:225], v[248:251], v[16:31]
	ds_read_b64_tr_b16 v[248:249], v197 offset:40448
	ds_read_b64_tr_b16 v[250:251], v197 offset:41600
	v_exp_f32_e32 v88, v88
	v_exp_f32_e32 v89, v89
	v_exp_f32_e32 v90, v90
	v_exp_f32_e32 v91, v91
	s_waitcnt lgkmcnt(2)
	v_mfma_f32_32x32x16_bf16 v[32:47], v[226:229], v[244:247], v[32:47]
	v_exp_f32_e32 v92, v92
	v_exp_f32_e32 v93, v93
	v_exp_f32_e32 v94, v94
	v_exp_f32_e32 v95, v95
	v_mfma_f32_32x32x16_bf16 v[48:63], v[226:229], v[184:187], v[48:63]
	v_cvt_pk_bf16_f32 v176, v120, v121
	v_cvt_pk_bf16_f32 v177, v122, v123
	v_cvt_pk_bf16_f32 v178, v124, v125
	v_cvt_pk_bf16_f32 v179, v126, v127
	v_cvt_pk_bf16_f32 v238, v80, v81
	v_cvt_pk_bf16_f32 v239, v82, v83
	v_cvt_pk_bf16_f32 v240, v84, v85
	v_cvt_pk_bf16_f32 v241, v86, v87
	v_mfma_f32_32x32x16_bf16 v[0:15], v[230:233], v[244:247], v[0:15]
	ds_read_b64_tr_b16 v[244:245], v197 offset:40512
	ds_read_b64_tr_b16 v[246:247], v197 offset:41664
	v_cvt_pk_bf16_f32 v180, v88, v89
	v_cvt_pk_bf16_f32 v181, v90, v91
	v_cvt_pk_bf16_f32 v182, v92, v93
	v_cvt_pk_bf16_f32 v183, v94, v95
	v_add_f32_e32 v164, v96, v164
	v_add_f32_e32 v165, v64, v165
	v_add_f32_e32 v164, v97, v164
	v_mfma_f32_32x32x16_bf16 v[16:31], v[230:233], v[184:187], v[16:31]
	ds_read_b64_tr_b16 v[184:185], v197 offset:42752
	ds_read_b64_tr_b16 v[186:187], v197 offset:43904
	v_add_f32_e32 v165, v65, v165
	v_add_f32_e32 v164, v98, v164
	v_add_f32_e32 v165, v66, v165
	v_add_f32_e32 v164, v99, v164
	v_add_f32_e32 v165, v67, v165
	s_waitcnt lgkmcnt(2)
	v_mfma_f32_32x32x16_bf16 v[32:47], v[234:237], v[248:251], v[32:47]
	v_add_f32_e32 v164, v100, v164
	v_add_f32_e32 v165, v68, v165
	v_add_f32_e32 v164, v101, v164
	v_add_f32_e32 v165, v69, v165
	v_add_f32_e32 v164, v102, v164
	v_add_f32_e32 v165, v70, v165
	v_mfma_f32_32x32x16_bf16 v[48:63], v[234:237], v[244:247], v[48:63]
	v_add_f32_e32 v164, v103, v164
	v_add_f32_e32 v165, v71, v165
	v_add_f32_e32 v164, v104, v164
	v_add_f32_e32 v165, v72, v165
	v_add_f32_e32 v164, v105, v164
	v_add_f32_e32 v165, v73, v165
	v_mfma_f32_32x32x16_bf16 v[0:15], v[238:241], v[248:251], v[0:15]
	ds_read_b64_tr_b16 v[248:249], v197 offset:42816
	ds_read_b64_tr_b16 v[250:251], v197 offset:43968
	v_add_f32_e32 v164, v106, v164
	v_add_f32_e32 v165, v74, v165
	v_add_f32_e32 v164, v107, v164
	v_add_f32_e32 v165, v75, v165
	v_add_f32_e32 v164, v108, v164
	v_mfma_f32_32x32x16_bf16 v[16:31], v[238:241], v[244:247], v[16:31]
	v_add_f32_e32 v165, v76, v165
	v_add_f32_e32 v164, v109, v164
	v_add_f32_e32 v165, v77, v165
	v_add_f32_e32 v164, v110, v164
	v_add_f32_e32 v165, v78, v165
	v_add_f32_e32 v164, v111, v164
	s_waitcnt lgkmcnt(0)
	v_mfma_f32_32x32x16_bf16 v[32:47], v[176:179], v[184:187], v[32:47]
	v_add_f32_e32 v165, v79, v165
	s_andn2_b64 vcc, exec, s[56:57]
	v_mfma_f32_32x32x16_bf16 v[48:63], v[176:179], v[248:251], v[48:63]
	s_cbranch_vccnz .Lr2b_nowriteB
	s_waitcnt vmcnt(0)
	ds_write_b128 v194, v[152:155] offset:0
	s_and_saveexec_b64 s[58:59], s[40:41]
	s_cbranch_execz .Lr2b_nok2wB
	ds_write_b128 v195, v[156:159] offset:0
.Lr2b_nok2wB:
	s_or_b64 exec, exec, s[58:59]
	ds_write_b128 v196, v[160:163] offset:26624
.Lr2b_nowriteB:
	v_mfma_f32_32x32x16_bf16 v[0:15], v[180:183], v[184:187], v[0:15]
	v_mfma_f32_32x32x16_bf16 v[16:31], v[180:183], v[248:251], v[16:31]
	s_cmp_lt_u32 s61, s28
	s_mov_b32 s62, s61
	s_waitcnt lgkmcnt(0)
	s_barrier
	s_cbranch_scc1 .Lr2b_topA
	v_add_f32_e32 v242, v112, v242
	v_add_f32_e32 v243, v80, v243
	v_add_f32_e32 v242, v113, v242
	v_add_f32_e32 v243, v81, v243
	v_add_f32_e32 v242, v114, v242
	v_add_f32_e32 v243, v82, v243
	v_add_f32_e32 v242, v115, v242
	v_add_f32_e32 v243, v83, v243
	v_add_f32_e32 v242, v116, v242
	v_add_f32_e32 v243, v84, v243
	v_add_f32_e32 v242, v117, v242
	v_add_f32_e32 v243, v85, v243
	v_add_f32_e32 v242, v118, v242
	v_add_f32_e32 v243, v86, v243
	v_add_f32_e32 v242, v119, v242
	v_add_f32_e32 v243, v87, v243
	v_add_f32_e32 v242, v120, v242
	v_add_f32_e32 v243, v88, v243
	v_add_f32_e32 v242, v121, v242
	v_add_f32_e32 v243, v89, v243
	v_add_f32_e32 v242, v122, v242
	v_add_f32_e32 v243, v90, v243
	v_add_f32_e32 v242, v123, v242
	v_add_f32_e32 v243, v91, v243
	v_add_f32_e32 v242, v124, v242
	v_add_f32_e32 v243, v92, v243
	v_add_f32_e32 v242, v125, v242
	v_add_f32_e32 v243, v93, v243
	v_add_f32_e32 v242, v126, v242
	v_add_f32_e32 v243, v94, v243
	v_add_f32_e32 v242, v127, v242
	v_add_f32_e32 v243, v95, v243
	v_add_f32_e32 v164, v164, v242
	v_add_f32_e32 v165, v165, v243
	v_mov_b32_e32 v244, v169
	v_mov_b32_e32 v245, v169
	v_mov_b32_e32 v246, v169
	v_mov_b32_e32 v247, v169
